# nt_p4
# baseline (speedup 1.0000x reference)
; #define PG8_STAGE(bufoff, gbase, voff) do { _Pragma("unroll") for (int _i = 0; _i < 2; ++_i) \
;         __builtin_amdgcn_global_load_lds((const unsigned*)((const char*)(gbase) + (voff)[_i]), (LAS unsigned*)(lds + (bufoff) + ldsw + _i * 8192), 16, 0, 0); } while (0)
; #define PG8_LDA(dst, b, h) do { _Pragma("unroll") for (int m = 0; m < 4; ++m) _Pragma("unroll") for (int k = 0; k < 2; ++k) dst[m][k] = *(const LAS bf16x8*)(lds + PG8_SA(b, h) + aoff + m * 2048 + k * 1024); } while (0)
; #define PG8_LDB(dst, b, h) do { _Pragma("unroll") for (int n = 0; n < 2; ++n) _Pragma("unroll") for (int k = 0; k < 2; ++k) dst[n][k] = *(const LAS bf16x8*)(lds + PG8_SB(b, h) + boff + n * 2048 + k * 1024); } while (0)
; #define PG8_MMA(ai, bj, At, Bt) do { __builtin_amdgcn_s_setprio(1); _Pragma("unroll") for (int m = 0; m < 4; ++m) _Pragma("unroll") for (int n = 0; n < 2; ++n) _Pragma("unroll") for (int k = 0; k < 2; ++k) \
;         acc[ai][bj][m][n] = __builtin_amdgcn_mfma_f32_16x16x32_bf16(Bt[n][k], At[m][k], acc[ai][bj][m][n], 0, 0, 0); __builtin_amdgcn_s_setprio(0); } while (0)
; #define PG8_WAIT_V(n) asm volatile("s_waitcnt vmcnt(" #n ")" ::: "memory")
; #define PG8_WAIT_L(n) asm volatile("s_waitcnt lgkmcnt(" #n ")" ::: "memory")
; #define PG8_BAR __builtin_amdgcn_s_barrier()
; #define PG8_SCHED __builtin_amdgcn_sched_barrier(0)
; template <class Epi, class Job>
; __device__ __forceinline__ void gemm_phase(LAS unsigned char* lds, const Job& S, const Epi& E) {
;     ...
;             PG8_LDB(B0, 0, 0); PG8_SCHED; PG8_LDA(At, 0, 0); PG8_STAGE(PG8_SA(1, 1), a1 + hstepA, voffA);
;             PG8_WAIT_L(8); PG8_BAR; PG8_WAIT_L(0); PG8_MMA(0, 0, At, B0); PG8_BAR; PG8_SCHED;
;             PG8_LDB(B1, 0, 1); PG8_STAGE(PG8_SB(0, 0), b2, voffB);
;             PG8_BAR; PG8_WAIT_L(0); PG8_MMA(0, 1, At, B1); PG8_BAR;
;             PG8_LDA(At, 0, 1); PG8_STAGE(PG8_SA(0, 0), a2, voffA);
;             PG8_BAR; PG8_WAIT_L(0); PG8_MMA(1, 0, At, B0); PG8_BAR; PG8_SCHED;
;             PG8_STAGE(PG8_SB(0, 1), b2 + hstepB, voffB);
;             PG8_WAIT_V(6); PG8_BAR; PG8_MMA(1, 1, At, B1); PG8_BAR;
.LBB0_457:
	s_add_i32 m0, s57, 0xc000
	s_nop 0
	global_load_lds_dwordx4 v132, s[36:37]
	s_add_i32 m0, s57, 0xe000
	s_nop 0
	global_load_lds_dwordx4 v142, s[36:37]
	s_add_u32 s46, s36, 0xfff00080
	s_addc_u32 s47, s37, -1
	s_cmp_eq_u32 s81, 60
	s_cselect_b32 s49, s29, s47
	s_cselect_b32 s48, s28, s46
	s_cselect_b32 s47, s31, s80
	s_cselect_b32 s46, s30, s79
	ds_read_b128 v[174:177], v151 offset:1024
	ds_read_b128 v[182:185], v151 offset:3072
	ds_read_b128 v[190:193], v151 offset:5120
	ds_read_b128 v[198:201], v151 offset:7168
	s_waitcnt lgkmcnt(8)
	s_waitcnt lgkmcnt(0)
	s_setprio 1
	s_barrier
	v_mfma_f32_16x16x32_bf16 v[124:127], v[154:157], v[170:173], v[124:127]
	ds_read_b128 v[202:205], v152
	v_mfma_f32_16x16x32_bf16 v[120:123], v[162:165], v[170:173], v[120:123]
	v_mfma_f32_16x16x32_bf16 v[116:119], v[154:157], v[178:181], v[116:119]
	ds_read_b128 v[206:209], v152 offset:1024
	v_mfma_f32_16x16x32_bf16 v[108:111], v[162:165], v[178:181], v[108:111]
	v_mfma_f32_16x16x32_bf16 v[100:103], v[154:157], v[186:189], v[100:103]
	ds_read_b128 v[210:213], v152 offset:2048
	v_mfma_f32_16x16x32_bf16 v[92:95], v[162:165], v[186:189], v[92:95]
	v_mfma_f32_16x16x32_bf16 v[84:87], v[154:157], v[194:197], v[84:87]
	ds_read_b128 v[214:217], v152 offset:3072
	v_mfma_f32_16x16x32_bf16 v[76:79], v[162:165], v[194:197], v[76:79]
	v_mfma_f32_16x16x32_bf16 v[124:127], v[158:161], v[174:177], v[124:127]
	v_mfma_f32_16x16x32_bf16 v[120:123], v[166:169], v[174:177], v[120:123]
	v_mfma_f32_16x16x32_bf16 v[116:119], v[158:161], v[182:185], v[116:119]
	v_mfma_f32_16x16x32_bf16 v[108:111], v[166:169], v[182:185], v[108:111]
	v_mfma_f32_16x16x32_bf16 v[100:103], v[158:161], v[190:193], v[100:103]
	v_mfma_f32_16x16x32_bf16 v[92:95], v[166:169], v[190:193], v[92:95]
	v_mfma_f32_16x16x32_bf16 v[84:87], v[158:161], v[198:201], v[84:87]
	v_mfma_f32_16x16x32_bf16 v[76:79], v[166:169], v[198:201], v[76:79]
	s_barrier
	s_setprio 0
	s_add_i32 s82, s66, s56
	s_mov_b32 m0, s82
	s_nop 0
	global_load_lds_dwordx4 v136, s[46:47]
	s_add_i32 m0, s82, 0x2000
	s_nop 0
	global_load_lds_dwordx4 v140, s[46:47]
	s_waitcnt lgkmcnt(0)
	s_setprio 1
	s_barrier
	v_mfma_f32_16x16x32_bf16 v[112:115], v[202:205], v[170:173], v[112:115]
	v_mfma_f32_16x16x32_bf16 v[104:107], v[210:213], v[170:173], v[104:107]
	v_mfma_f32_16x16x32_bf16 v[96:99], v[202:205], v[178:181], v[96:99]
	v_mfma_f32_16x16x32_bf16 v[88:91], v[210:213], v[178:181], v[88:91]
	v_mfma_f32_16x16x32_bf16 v[80:83], v[202:205], v[186:189], v[80:83]
	v_mfma_f32_16x16x32_bf16 v[72:75], v[210:213], v[186:189], v[72:75]
	v_mfma_f32_16x16x32_bf16 v[68:71], v[202:205], v[194:197], v[68:71]
	v_mfma_f32_16x16x32_bf16 v[64:67], v[210:213], v[194:197], v[64:67]
	v_mfma_f32_16x16x32_bf16 v[112:115], v[206:209], v[174:177], v[112:115]
	ds_read_b128 v[170:173], v151 offset:16384
	v_mfma_f32_16x16x32_bf16 v[104:107], v[214:217], v[174:177], v[104:107]
	v_mfma_f32_16x16x32_bf16 v[96:99], v[206:209], v[182:185], v[96:99]
	ds_read_b128 v[178:181], v151 offset:18432
	v_mfma_f32_16x16x32_bf16 v[88:91], v[214:217], v[182:185], v[88:91]
	v_mfma_f32_16x16x32_bf16 v[80:83], v[206:209], v[190:193], v[80:83]
	ds_read_b128 v[186:189], v151 offset:20480
	v_mfma_f32_16x16x32_bf16 v[72:75], v[214:217], v[190:193], v[72:75]
	v_mfma_f32_16x16x32_bf16 v[68:71], v[206:209], v[198:201], v[68:71]
	ds_read_b128 v[194:197], v151 offset:22528
	v_mfma_f32_16x16x32_bf16 v[64:67], v[214:217], v[198:201], v[64:67]
	s_barrier
	s_setprio 0
	s_mov_b32 m0, s57
	s_mov_b64 s[100:101], s[48:49]
	global_load_lds_dwordx4 v134, s[48:49]
	s_mov_b32 m0, s58
	s_nop 0
	global_load_lds_dwordx4 v138, s[48:49]
	ds_read_b128 v[174:177], v151 offset:17408
	ds_read_b128 v[182:185], v151 offset:19456
	ds_read_b128 v[190:193], v151 offset:21504
	ds_read_b128 v[198:201], v151 offset:23552
	s_waitcnt vmcnt(8)
	s_waitcnt lgkmcnt(0)
	s_setprio 1
	s_barrier
	v_mfma_f32_16x16x32_bf16 v[60:63], v[154:157], v[170:173], v[60:63]
	v_mfma_f32_16x16x32_bf16 v[56:59], v[162:165], v[170:173], v[56:59]
	v_mfma_f32_16x16x32_bf16 v[52:55], v[154:157], v[178:181], v[52:55]
	v_mfma_f32_16x16x32_bf16 v[44:47], v[162:165], v[178:181], v[44:47]
	v_mfma_f32_16x16x32_bf16 v[36:39], v[154:157], v[186:189], v[36:39]
	v_mfma_f32_16x16x32_bf16 v[28:31], v[162:165], v[186:189], v[28:31]
	v_mfma_f32_16x16x32_bf16 v[20:23], v[154:157], v[194:197], v[20:23]
	v_mfma_f32_16x16x32_bf16 v[12:15], v[162:165], v[194:197], v[12:15]
	v_mfma_f32_16x16x32_bf16 v[60:63], v[158:161], v[174:177], v[60:63]
	v_mfma_f32_16x16x32_bf16 v[56:59], v[166:169], v[174:177], v[56:59]
	v_mfma_f32_16x16x32_bf16 v[52:55], v[158:161], v[182:185], v[52:55]
	v_mfma_f32_16x16x32_bf16 v[44:47], v[166:169], v[182:185], v[44:47]
	v_mfma_f32_16x16x32_bf16 v[36:39], v[158:161], v[190:193], v[36:39]
	v_mfma_f32_16x16x32_bf16 v[28:31], v[166:169], v[190:193], v[28:31]
	v_mfma_f32_16x16x32_bf16 v[20:23], v[158:161], v[198:201], v[20:23]
	v_mfma_f32_16x16x32_bf16 v[12:15], v[166:169], v[198:201], v[12:15]
	s_barrier
	s_setprio 0
	s_add_u32 s82, s46, 0x100000
	s_addc_u32 s83, s47, 0
	s_add_i32 s84, s67, s56
	s_mov_b32 m0, s84
	s_nop 0
	global_load_lds_dwordx4 v136, s[82:83]
	s_add_i32 m0, s84, 0x2000
	s_nop 0
	global_load_lds_dwordx4 v140, s[82:83]
	s_waitcnt vmcnt(6)
	s_setprio 1
	v_add_u32_e32 v153, 0x18000, v148
	s_barrier
; #define PG8_STAGE(bufoff, gbase, voff) do { _Pragma("unroll") for (int _i = 0; _i < 2; ++_i) \
;         __builtin_amdgcn_global_load_lds((const unsigned*)((const char*)(gbase) + (voff)[_i]), (LAS unsigned*)(lds + (bufoff) + ldsw + _i * 8192), 16, 0, 0); } while (0)
; #define PG8_LDA(dst, b, h) do { _Pragma("unroll") for (int m = 0; m < 4; ++m) _Pragma("unroll") for (int k = 0; k < 2; ++k) dst[m][k] = *(const LAS bf16x8*)(lds + PG8_SA(b, h) + aoff + m * 2048 + k * 1024); } while (0)
; #define PG8_LDB(dst, b, h) do { _Pragma("unroll") for (int n = 0; n < 2; ++n) _Pragma("unroll") for (int k = 0; k < 2; ++k) dst[n][k] = *(const LAS bf16x8*)(lds + PG8_SB(b, h) + boff + n * 2048 + k * 1024); } while (0)
; #define PG8_MMA(ai, bj, At, Bt) do { __builtin_amdgcn_s_setprio(1); _Pragma("unroll") for (int m = 0; m < 4; ++m) _Pragma("unroll") for (int n = 0; n < 2; ++n) _Pragma("unroll") for (int k = 0; k < 2; ++k) \
;         acc[ai][bj][m][n] = __builtin_amdgcn_mfma_f32_16x16x32_bf16(Bt[n][k], At[m][k], acc[ai][bj][m][n], 0, 0, 0); __builtin_amdgcn_s_setprio(0); } while (0)
; #define PG8_WAIT_V(n) asm volatile("s_waitcnt vmcnt(" #n ")" ::: "memory")
; #define PG8_WAIT_L(n) asm volatile("s_waitcnt lgkmcnt(" #n ")" ::: "memory")
; #define PG8_BAR __builtin_amdgcn_s_barrier()
; #define PG8_SCHED __builtin_amdgcn_sched_barrier(0)
; template <class Epi, class Job>
; __device__ __forceinline__ void gemm_phase(LAS unsigned char* lds, const Job& S, const Epi& E) {
;     ...
;             PG8_WAIT_V(6); PG8_BAR; PG8_MMA(1, 1, At, B1); PG8_BAR;
;             PG8_LDB(B0, 1, 0); PG8_SCHED; PG8_LDA(At, 1, 0); PG8_STAGE(PG8_SA(0, 1), a2 + hstepA, voffA);
;             PG8_WAIT_L(8); PG8_BAR; PG8_WAIT_L(0); PG8_MMA(0, 0, At, B0); PG8_BAR; PG8_SCHED;
;             PG8_LDB(B1, 1, 1); PG8_STAGE(PG8_SB(1, 0), b3, voffB);
;             PG8_BAR; PG8_WAIT_L(0); PG8_MMA(0, 1, At, B1); PG8_BAR;
;             PG8_LDA(At, 1, 1); PG8_STAGE(PG8_SA(1, 0), a3, voffA);
	v_mfma_f32_16x16x32_bf16 v[48:51], v[202:205], v[170:173], v[48:51]
	ds_read_b128 v[154:157], v153
	v_mfma_f32_16x16x32_bf16 v[40:43], v[210:213], v[170:173], v[40:43]
	v_mfma_f32_16x16x32_bf16 v[32:35], v[202:205], v[178:181], v[32:35]
	ds_read_b128 v[158:161], v153 offset:1024
	v_mfma_f32_16x16x32_bf16 v[24:27], v[210:213], v[178:181], v[24:27]
	v_mfma_f32_16x16x32_bf16 v[16:19], v[202:205], v[186:189], v[16:19]
	ds_read_b128 v[162:165], v153 offset:2048
	v_mfma_f32_16x16x32_bf16 v[8:11], v[210:213], v[186:189], v[8:11]
	v_mfma_f32_16x16x32_bf16 v[4:7], v[202:205], v[194:197], v[4:7]
	ds_read_b128 v[166:169], v153 offset:3072
	v_mfma_f32_16x16x32_bf16 v[0:3], v[210:213], v[194:197], v[0:3]
	v_mfma_f32_16x16x32_bf16 v[48:51], v[206:209], v[174:177], v[48:51]
	ds_read_b128 v[170:173], v151 offset:32768
	v_mfma_f32_16x16x32_bf16 v[40:43], v[214:217], v[174:177], v[40:43]
	v_mfma_f32_16x16x32_bf16 v[32:35], v[206:209], v[182:185], v[32:35]
	ds_read_b128 v[178:181], v151 offset:34816
	v_mfma_f32_16x16x32_bf16 v[24:27], v[214:217], v[182:185], v[24:27]
	v_mfma_f32_16x16x32_bf16 v[16:19], v[206:209], v[190:193], v[16:19]
	ds_read_b128 v[186:189], v151 offset:36864
	v_mfma_f32_16x16x32_bf16 v[8:11], v[214:217], v[190:193], v[8:11]
	v_mfma_f32_16x16x32_bf16 v[4:7], v[206:209], v[198:201], v[4:7]
	ds_read_b128 v[194:197], v151 offset:38912
	v_mfma_f32_16x16x32_bf16 v[0:3], v[214:217], v[198:201], v[0:3]
	s_barrier
	s_setprio 0
	s_add_i32 s82, 0, 0x18000
	v_add_u32_e32 v153, s82, v148
	s_add_u32 s48, s48, 0x100000
	s_addc_u32 s49, s49, 0
	s_mov_b32 m0, s59
	s_nop 0
	global_load_lds_dwordx4 v134, s[48:49]
	s_mov_b32 m0, s60
	s_nop 0
	global_load_lds_dwordx4 v138, s[48:49]
	ds_read_b128 v[174:177], v151 offset:33792
	ds_read_b128 v[182:185], v151 offset:35840
	ds_read_b128 v[190:193], v151 offset:37888
	ds_read_b128 v[198:201], v151 offset:39936
	s_waitcnt lgkmcnt(8)
	s_waitcnt lgkmcnt(0)
	s_setprio 1
	v_add_u32_e32 v153, 0x1c000, v148
	s_barrier
	v_mfma_f32_16x16x32_bf16 v[124:127], v[154:157], v[170:173], v[124:127]
	ds_read_b128 v[202:205], v153
	v_mfma_f32_16x16x32_bf16 v[120:123], v[162:165], v[170:173], v[120:123]
	v_mfma_f32_16x16x32_bf16 v[116:119], v[154:157], v[178:181], v[116:119]
	ds_read_b128 v[206:209], v153 offset:1024
	v_mfma_f32_16x16x32_bf16 v[108:111], v[162:165], v[178:181], v[108:111]
	v_mfma_f32_16x16x32_bf16 v[100:103], v[154:157], v[186:189], v[100:103]
	ds_read_b128 v[210:213], v153 offset:2048
	v_mfma_f32_16x16x32_bf16 v[92:95], v[162:165], v[186:189], v[92:95]
	v_mfma_f32_16x16x32_bf16 v[84:87], v[154:157], v[194:197], v[84:87]
	ds_read_b128 v[214:217], v153 offset:3072
	v_mfma_f32_16x16x32_bf16 v[76:79], v[162:165], v[194:197], v[76:79]
	v_mfma_f32_16x16x32_bf16 v[124:127], v[158:161], v[174:177], v[124:127]
	v_mfma_f32_16x16x32_bf16 v[120:123], v[166:169], v[174:177], v[120:123]
	v_mfma_f32_16x16x32_bf16 v[116:119], v[158:161], v[182:185], v[116:119]
	v_mfma_f32_16x16x32_bf16 v[108:111], v[166:169], v[182:185], v[108:111]
	v_mfma_f32_16x16x32_bf16 v[100:103], v[158:161], v[190:193], v[100:103]
	v_mfma_f32_16x16x32_bf16 v[92:95], v[166:169], v[190:193], v[92:95]
	v_mfma_f32_16x16x32_bf16 v[84:87], v[158:161], v[198:201], v[84:87]
	v_mfma_f32_16x16x32_bf16 v[76:79], v[166:169], v[198:201], v[76:79]
	s_barrier
	s_setprio 0
	s_add_i32 s48, 0, 0x1c000
	s_add_i32 s49, s82, s56
	v_add_u32_e32 v153, s48, v148
	s_add_u32 s98, s46, s8
	s_addc_u32 s99, s47, s9
	s_mov_b32 m0, s49
	s_nop 0
	global_load_lds_dwordx4 v136, s[98:99]
	s_add_i32 m0, s49, 0x2000
	s_nop 0
	global_load_lds_dwordx4 v140, s[98:99]
	s_waitcnt lgkmcnt(0)
	s_setprio 1
	s_barrier
	v_mfma_f32_16x16x32_bf16 v[112:115], v[202:205], v[170:173], v[112:115]
	v_mfma_f32_16x16x32_bf16 v[104:107], v[210:213], v[170:173], v[104:107]
	v_mfma_f32_16x16x32_bf16 v[96:99], v[202:205], v[178:181], v[96:99]
	v_mfma_f32_16x16x32_bf16 v[88:91], v[210:213], v[178:181], v[88:91]
	v_mfma_f32_16x16x32_bf16 v[80:83], v[202:205], v[186:189], v[80:83]
	v_mfma_f32_16x16x32_bf16 v[72:75], v[210:213], v[186:189], v[72:75]
	v_mfma_f32_16x16x32_bf16 v[68:71], v[202:205], v[194:197], v[68:71]
	v_mfma_f32_16x16x32_bf16 v[64:67], v[210:213], v[194:197], v[64:67]
	v_mfma_f32_16x16x32_bf16 v[112:115], v[206:209], v[174:177], v[112:115]
	ds_read_b128 v[170:173], v151 offset:49152
	v_mfma_f32_16x16x32_bf16 v[104:107], v[214:217], v[174:177], v[104:107]
	v_mfma_f32_16x16x32_bf16 v[96:99], v[206:209], v[182:185], v[96:99]
	ds_read_b128 v[178:181], v151 offset:51200
	v_mfma_f32_16x16x32_bf16 v[88:91], v[214:217], v[182:185], v[88:91]
	v_mfma_f32_16x16x32_bf16 v[80:83], v[206:209], v[190:193], v[80:83]
	ds_read_b128 v[186:189], v151 offset:53248
	v_mfma_f32_16x16x32_bf16 v[72:75], v[214:217], v[190:193], v[72:75]
	v_mfma_f32_16x16x32_bf16 v[68:71], v[206:209], v[198:201], v[68:71]
	ds_read_b128 v[194:197], v151 offset:55296
	v_mfma_f32_16x16x32_bf16 v[64:67], v[214:217], v[198:201], v[64:67]
	s_barrier
	s_setprio 0
	s_mov_b32 m0, s62
	s_add_u32 s100, s100, s8
	s_addc_u32 s101, s101, s9
	global_load_lds_dwordx4 v134, s[100:101]
	s_mov_b32 m0, s63
	s_nop 0
	global_load_lds_dwordx4 v138, s[100:101]
	ds_read_b128 v[174:177], v151 offset:50176
	ds_read_b128 v[182:185], v151 offset:52224
	ds_read_b128 v[190:193], v151 offset:54272
	ds_read_b128 v[198:201], v151 offset:56320
	s_waitcnt vmcnt(8)
	s_waitcnt lgkmcnt(0)
	s_setprio 1
	s_barrier
; #define PG8_STAGE(bufoff, gbase, voff) do { _Pragma("unroll") for (int _i = 0; _i < 2; ++_i) \
;         __builtin_amdgcn_global_load_lds((const unsigned*)((const char*)(gbase) + (voff)[_i]), (LAS unsigned*)(lds + (bufoff) + ldsw + _i * 8192), 16, 0, 0); } while (0)
; #define PG8_MMA(ai, bj, At, Bt) do { __builtin_amdgcn_s_setprio(1); _Pragma("unroll") for (int m = 0; m < 4; ++m) _Pragma("unroll") for (int n = 0; n < 2; ++n) _Pragma("unroll") for (int k = 0; k < 2; ++k) \
;         acc[ai][bj][m][n] = __builtin_amdgcn_mfma_f32_16x16x32_bf16(Bt[n][k], At[m][k], acc[ai][bj][m][n], 0, 0, 0); __builtin_amdgcn_s_setprio(0); } while (0)
; #define PG8_WAIT_V(n) asm volatile("s_waitcnt vmcnt(" #n ")" ::: "memory")
; #define PG8_WAIT_L(n) asm volatile("s_waitcnt lgkmcnt(" #n ")" ::: "memory")
; #define PG8_BAR __builtin_amdgcn_s_barrier()
; #define PG8_SCHED __builtin_amdgcn_sched_barrier(0)
; template <class Epi, class Job>
; __device__ __forceinline__ void gemm_phase(LAS unsigned char* lds, const Job& S, const Epi& E) {
;     ...
;             PG8_BAR; PG8_WAIT_L(0); PG8_MMA(1, 0, At, B0); PG8_BAR; PG8_SCHED;
;             PG8_STAGE(PG8_SB(1, 1), b3 + hstepB, voffB);
;             PG8_WAIT_V(6); PG8_BAR; PG8_MMA(1, 1, At, B1); PG8_BAR;
;         }
	v_mfma_f32_16x16x32_bf16 v[60:63], v[154:157], v[170:173], v[60:63]
	v_mfma_f32_16x16x32_bf16 v[56:59], v[162:165], v[170:173], v[56:59]
	v_mfma_f32_16x16x32_bf16 v[52:55], v[154:157], v[178:181], v[52:55]
	v_mfma_f32_16x16x32_bf16 v[44:47], v[162:165], v[178:181], v[44:47]
	v_mfma_f32_16x16x32_bf16 v[36:39], v[154:157], v[186:189], v[36:39]
	v_mfma_f32_16x16x32_bf16 v[28:31], v[162:165], v[186:189], v[28:31]
	v_mfma_f32_16x16x32_bf16 v[20:23], v[154:157], v[194:197], v[20:23]
	v_mfma_f32_16x16x32_bf16 v[12:15], v[162:165], v[194:197], v[12:15]
	v_mfma_f32_16x16x32_bf16 v[60:63], v[158:161], v[174:177], v[60:63]
	v_mfma_f32_16x16x32_bf16 v[56:59], v[166:169], v[174:177], v[56:59]
	v_mfma_f32_16x16x32_bf16 v[52:55], v[158:161], v[182:185], v[52:55]
	v_mfma_f32_16x16x32_bf16 v[44:47], v[166:169], v[182:185], v[44:47]
	v_mfma_f32_16x16x32_bf16 v[36:39], v[158:161], v[190:193], v[36:39]
	v_mfma_f32_16x16x32_bf16 v[28:31], v[166:169], v[190:193], v[28:31]
	v_mfma_f32_16x16x32_bf16 v[20:23], v[158:161], v[198:201], v[20:23]
	v_mfma_f32_16x16x32_bf16 v[12:15], v[166:169], v[198:201], v[12:15]
	s_barrier
	s_setprio 0
	s_add_u32 s46, s46, 0x100080
	s_addc_u32 s47, s47, 0
	s_add_i32 s48, s48, s56
	s_mov_b32 m0, s48
	s_nop 0
	global_load_lds_dwordx4 v136, s[46:47]
	s_add_i32 m0, s48, 0x2000
	s_nop 0
	global_load_lds_dwordx4 v140, s[46:47]
	s_waitcnt vmcnt(6)
	s_setprio 1
	s_barrier
	v_mfma_f32_16x16x32_bf16 v[48:51], v[202:205], v[170:173], v[48:51]
	ds_read_b128 v[154:157], v150
	v_mfma_f32_16x16x32_bf16 v[40:43], v[210:213], v[170:173], v[40:43]
	v_mfma_f32_16x16x32_bf16 v[32:35], v[202:205], v[178:181], v[32:35]
	ds_read_b128 v[158:161], v150 offset:1024
	v_mfma_f32_16x16x32_bf16 v[24:27], v[210:213], v[178:181], v[24:27]
	v_mfma_f32_16x16x32_bf16 v[16:19], v[202:205], v[186:189], v[16:19]
	ds_read_b128 v[162:165], v150 offset:2048
	v_mfma_f32_16x16x32_bf16 v[8:11], v[210:213], v[186:189], v[8:11]
	v_mfma_f32_16x16x32_bf16 v[4:7], v[202:205], v[194:197], v[4:7]
	ds_read_b128 v[166:169], v150 offset:3072
	v_mfma_f32_16x16x32_bf16 v[0:3], v[210:213], v[194:197], v[0:3]
	v_mfma_f32_16x16x32_bf16 v[48:51], v[206:209], v[174:177], v[48:51]
	ds_read_b128 v[170:173], v151
	v_mfma_f32_16x16x32_bf16 v[40:43], v[214:217], v[174:177], v[40:43]
	v_mfma_f32_16x16x32_bf16 v[32:35], v[206:209], v[182:185], v[32:35]
	ds_read_b128 v[178:181], v151 offset:2048
	v_mfma_f32_16x16x32_bf16 v[24:27], v[214:217], v[182:185], v[24:27]
	v_mfma_f32_16x16x32_bf16 v[16:19], v[206:209], v[190:193], v[16:19]
	ds_read_b128 v[186:189], v151 offset:4096
	v_mfma_f32_16x16x32_bf16 v[8:11], v[214:217], v[190:193], v[8:11]
	v_mfma_f32_16x16x32_bf16 v[4:7], v[206:209], v[198:201], v[4:7]
	ds_read_b128 v[194:197], v151 offset:6144
	v_mfma_f32_16x16x32_bf16 v[0:3], v[214:217], v[198:201], v[0:3]
	s_barrier
	s_setprio 0
	s_add_i32 s81, s81, 2
	s_add_u32 s36, s36, 0x100
	s_addc_u32 s37, s37, 0
	s_add_u32 s79, s79, 0x100
	s_addc_u32 s80, s80, 0
	s_cmp_gt_u32 s81, 61
	s_cbranch_scc0 .LBB0_457
; __device__ __forceinline__ unsigned cvt_pk_bf16(float lo, float hi) { unsigned r; asm volatile("v_cvt_pk_bf16_f32 %0, %1, %2" : "=v"(r) : "v"(lo), "v"(hi)); return r; }
;     __device__ __forceinline__ void operator()(const f32x4 (&acc)[2][2][4][2], const Unit& u, int wr, int wc, int fr, int fq) const {
;         const int row0 = u.orow + wr * 64 + fr, col0 = u.ocol + wc * 32 + 8 * fq;
; #pragma unroll
;         for (int ai = 0; ai < 2; ++ai)
; #pragma unroll
;             for (int m = 0; m < 4; ++m) { bf16_t* rowp = O + (size_t)(row0 + ai * HALF + m * 16) * ldc + col0;
; #pragma unroll
;                 for (int bj = 0; bj < 2; ++bj) { const f32x4 v0 = acc[ai][bj][m][0], v1 = acc[ai][bj][m][1];
;                     u32x4 w; w.x = cvt_pk_bf16(v0[0], v0[1]); w.y = cvt_pk_bf16(v0[2], v0[3]); w.z = cvt_pk_bf16(v1[0], v1[1]); w.w = cvt_pk_bf16(v1[2], v1[3]);
;                     if (nt) __builtin_nontemporal_store(w, (u32x4*)(rowp + bj * HALF)); else *(u32x4*)(rowp + bj * HALF) = w; } }
	s_waitcnt lgkmcnt(0)
	v_add_u32_e32 v146, s78, v131
	v_ashrrev_i32_e32 v147, 31, v146
	v_add_u32_e32 v154, s77, v149
	v_lshlrev_b64 v[146:147], 13, v[146:147]
	v_ashrrev_i32_e32 v155, 31, v154
	v_lshl_add_u64 v[146:147], s[18:19], 0, v[146:147]
	v_lshl_add_u64 v[146:147], v[154:155], 1, v[146:147]
	v_cvt_pk_bf16_f32 v124, v124, v125
	v_cvt_pk_bf16_f32 v125, v126, v127
	v_cvt_pk_bf16_f32 v126, v120, v121
	v_cvt_pk_bf16_f32 v127, v122, v123
	global_store_dwordx4 v[146:147], v[124:127], off nt
	v_cvt_pk_bf16_f32 v112, v112, v113
	v_cvt_pk_bf16_f32 v113, v114, v115
	v_cvt_pk_bf16_f32 v114, v104, v105
	v_cvt_pk_bf16_f32 v115, v106, v107
	global_store_dwordx4 v[146:147], v[112:115], off offset:256 nt
	v_cvt_pk_bf16_f32 v104, v116, v117
	v_cvt_pk_bf16_f32 v105, v118, v119
	v_cvt_pk_bf16_f32 v106, v108, v109
	v_add_co_u32_e32 v108, vcc, s68, v146
	s_nop 0
	v_lshl_add_u64 v[112:113], v[146:147], 0, s[10:11]
	v_addc_co_u32_e32 v109, vcc, 0, v147, vcc
	v_cvt_pk_bf16_f32 v107, v110, v111
	global_store_dwordx4 v[108:109], v[104:107], off nt
	v_cvt_pk_bf16_f32 v96, v96, v97
	v_cvt_pk_bf16_f32 v97, v98, v99
	v_cvt_pk_bf16_f32 v98, v88, v89
	v_cvt_pk_bf16_f32 v99, v90, v91
	global_store_dwordx4 v[112:113], v[96:99], off offset:256 nt
	v_cvt_pk_bf16_f32 v88, v100, v101
	v_cvt_pk_bf16_f32 v89, v102, v103
	v_cvt_pk_bf16_f32 v90, v92, v93
	v_add_co_u32_e32 v92, vcc, s69, v146
	s_nop 0
	v_lshl_add_u64 v[96:97], v[146:147], 0, s[12:13]
	v_addc_co_u32_e32 v93, vcc, 0, v147, vcc
	v_cvt_pk_bf16_f32 v91, v94, v95
	global_store_dwordx4 v[92:93], v[88:91], off nt
	v_cvt_pk_bf16_f32 v80, v80, v81
	v_cvt_pk_bf16_f32 v81, v82, v83
	v_cvt_pk_bf16_f32 v82, v72, v73
	v_cvt_pk_bf16_f32 v83, v74, v75
	global_store_dwordx4 v[96:97], v[80:83], off offset:256 nt
	v_cvt_pk_bf16_f32 v72, v84, v85
	v_cvt_pk_bf16_f32 v73, v86, v87
	v_cvt_pk_bf16_f32 v74, v76, v77
	v_add_co_u32_e32 v76, vcc, s70, v146
	s_nop 0
	v_lshl_add_u64 v[80:81], v[146:147], 0, s[20:21]
	v_addc_co_u32_e32 v77, vcc, 0, v147, vcc
	v_cvt_pk_bf16_f32 v75, v78, v79
	global_store_dwordx4 v[76:77], v[72:75], off nt
	v_cvt_pk_bf16_f32 v68, v68, v69
	v_cvt_pk_bf16_f32 v69, v70, v71
	v_cvt_pk_bf16_f32 v70, v64, v65
	v_cvt_pk_bf16_f32 v71, v66, v67
	global_store_dwordx4 v[80:81], v[68:71], off offset:256 nt
	v_cvt_pk_bf16_f32 v60, v60, v61
	v_cvt_pk_bf16_f32 v61, v62, v63
	v_cvt_pk_bf16_f32 v62, v56, v57
	v_add_co_u32_e32 v56, vcc, s71, v146
	v_lshl_add_u64 v[64:65], v[146:147], 0, s[6:7]
	s_nop 0
	v_addc_co_u32_e32 v57, vcc, 0, v147, vcc
	v_cvt_pk_bf16_f32 v63, v58, v59
	global_store_dwordx4 v[56:57], v[60:63], off nt
	v_cvt_pk_bf16_f32 v48, v48, v49
	v_cvt_pk_bf16_f32 v49, v50, v51
	v_cvt_pk_bf16_f32 v50, v40, v41
	v_cvt_pk_bf16_f32 v51, v42, v43
	global_store_dwordx4 v[64:65], v[48:51], off offset:256 nt
	v_cvt_pk_bf16_f32 v40, v52, v53
	v_cvt_pk_bf16_f32 v41, v54, v55
	v_cvt_pk_bf16_f32 v42, v44, v45
	v_add_co_u32_e32 v44, vcc, s72, v146
	s_nop 0
	v_lshl_add_u64 v[48:49], v[146:147], 0, s[22:23]
	v_addc_co_u32_e32 v45, vcc, 0, v147, vcc
	v_cvt_pk_bf16_f32 v43, v46, v47
	global_store_dwordx4 v[44:45], v[40:43], off nt
	v_cvt_pk_bf16_f32 v32, v32, v33
	v_cvt_pk_bf16_f32 v33, v34, v35
	v_cvt_pk_bf16_f32 v34, v24, v25
	v_cvt_pk_bf16_f32 v35, v26, v27
	global_store_dwordx4 v[48:49], v[32:35], off offset:256 nt
	v_cvt_pk_bf16_f32 v24, v36, v37
	v_cvt_pk_bf16_f32 v25, v38, v39
	v_cvt_pk_bf16_f32 v26, v28, v29
	v_add_co_u32_e32 v28, vcc, s73, v146
	s_nop 0
	v_lshl_add_u64 v[32:33], v[146:147], 0, s[24:25]
	v_addc_co_u32_e32 v29, vcc, 0, v147, vcc
	v_cvt_pk_bf16_f32 v27, v30, v31
	global_store_dwordx4 v[28:29], v[24:27], off nt
	v_cvt_pk_bf16_f32 v16, v16, v17
	v_cvt_pk_bf16_f32 v17, v18, v19
	v_cvt_pk_bf16_f32 v18, v8, v9
	v_cvt_pk_bf16_f32 v19, v10, v11
	global_store_dwordx4 v[32:33], v[16:19], off offset:256 nt
	v_cvt_pk_bf16_f32 v8, v20, v21
	v_cvt_pk_bf16_f32 v9, v22, v23
	v_cvt_pk_bf16_f32 v10, v12, v13
	v_add_co_u32_e32 v12, vcc, s74, v146
	s_nop 0
	v_lshl_add_u64 v[16:17], v[146:147], 0, s[26:27]
	v_addc_co_u32_e32 v13, vcc, 0, v147, vcc
	s_and_b64 vcc, exec, s[4:5]
	s_mov_b32 s77, s76
	s_mov_b32 s78, s75
	s_mov_b64 s[46:47], s[30:31]
	s_mov_b64 s[36:37], s[28:29]
	v_cvt_pk_bf16_f32 v11, v14, v15
	global_store_dwordx4 v[12:13], v[8:11], off nt
	v_cvt_pk_bf16_f32 v4, v4, v5
	v_cvt_pk_bf16_f32 v5, v6, v7
	v_cvt_pk_bf16_f32 v6, v0, v1
	v_cvt_pk_bf16_f32 v7, v2, v3
	global_store_dwordx4 v[16:17], v[4:7], off offset:256 nt
	s_cbranch_vccz .LBB0_450
	s_waitcnt vmcnt(0)
	s_cmpk_gt_u32 s50, 0xff
	s_cbranch_scc1 .LBB0_461
	s_barrier
